# scan1 own-tile loop: all 16 loads of a step group issued before the first wait (consumers of the first loads moved behind the last load)
# speedup vs baseline: 1.0017x; 1.0017x over previous
; __device__ __forceinline__ float bf_lo(unsigned w) { return __uint_as_float(w << 16); }
; __device__ __forceinline__ float bf_hi(unsigned w) { return __uint_as_float(w & 0xffff0000u); }
; __device__ __forceinline__ void scan1_own_tiles(const unsigned* AU, float* PA, float* PH) {
;     ...
;             for (int t = 0; t < SCL; ++t) { const u32x2 w = *(const u32x2*)(AU + base + (size_t)t * DM);
;                 const float a0 = 1.0f - bf_lo(w.x), a1 = 1.0f - bf_lo(w.y);
;                 h0 = a0 * h0 + bf_hi(w.x); h1 = a1 * h1 + bf_hi(w.y); p0 *= a0; p1 *= a1; }
.LBB0_959:
	v_lshl_add_u64 v[10:11], v[4:5], 0, s[42:43]
	v_add_co_u32_e32 v18, vcc, 0x24500000, v10
	s_add_u32 s42, s42, 0x20000
	s_nop 0
	v_addc_co_u32_e32 v19, vcc, 0, v11, vcc
	v_add_co_u32_e32 v20, vcc, s44, v10
	s_addc_u32 s43, s43, 0
	s_nop 0
	v_addc_co_u32_e32 v21, vcc, 0, v11, vcc
	v_add_co_u32_e32 v22, vcc, s45, v10
	global_load_dwordx2 v[18:19], v[18:19], off
	s_nop 0
	global_load_dwordx2 v[20:21], v[20:21], off
	v_addc_co_u32_e32 v23, vcc, 0, v11, vcc
	v_add_co_u32_e32 v24, vcc, s46, v10
	s_cmp_eq_u32 s42, 0x100000
	s_nop 0
	v_addc_co_u32_e32 v25, vcc, 0, v11, vcc
	v_add_co_u32_e32 v26, vcc, s47, v10
	global_load_dwordx2 v[22:23], v[22:23], off
	s_nop 0
	global_load_dwordx2 v[24:25], v[24:25], off
	v_addc_co_u32_e32 v27, vcc, 0, v11, vcc
	v_add_co_u32_e32 v28, vcc, s48, v10
	s_nop 0
	s_nop 0
	v_addc_co_u32_e32 v29, vcc, 0, v11, vcc
	v_add_co_u32_e32 v30, vcc, s49, v10
	global_load_dwordx2 v[26:27], v[26:27], off
	s_nop 0
	global_load_dwordx2 v[28:29], v[28:29], off
	v_addc_co_u32_e32 v31, vcc, 0, v11, vcc
	v_add_co_u32_e32 v32, vcc, s50, v10
	s_nop 0
	s_nop 0
	v_addc_co_u32_e32 v33, vcc, 0, v11, vcc
	v_add_co_u32_e32 v34, vcc, s51, v10
	global_load_dwordx2 v[30:31], v[30:31], off
	s_nop 0
	global_load_dwordx2 v[32:33], v[32:33], off
	v_addc_co_u32_e32 v35, vcc, 0, v11, vcc
	v_add_co_u32_e32 v36, vcc, s52, v10
	s_nop 0
	s_nop 0
	v_addc_co_u32_e32 v37, vcc, 0, v11, vcc
	v_add_co_u32_e32 v38, vcc, s53, v10
	global_load_dwordx2 v[34:35], v[34:35], off
	s_nop 0
	global_load_dwordx2 v[36:37], v[36:37], off
	v_addc_co_u32_e32 v39, vcc, 0, v11, vcc
	v_add_co_u32_e32 v40, vcc, s54, v10
	s_nop 0
	s_nop 0
	v_addc_co_u32_e32 v41, vcc, 0, v11, vcc
	v_add_co_u32_e32 v42, vcc, s55, v10
	global_load_dwordx2 v[38:39], v[38:39], off
	s_nop 0
	global_load_dwordx2 v[40:41], v[40:41], off
	v_addc_co_u32_e32 v43, vcc, 0, v11, vcc
	v_add_co_u32_e32 v44, vcc, s56, v10
	s_nop 0
	s_nop 0
	v_addc_co_u32_e32 v45, vcc, 0, v11, vcc
	v_add_co_u32_e32 v46, vcc, s57, v10
	global_load_dwordx2 v[42:43], v[42:43], off
	s_nop 0
	global_load_dwordx2 v[44:45], v[44:45], off
	v_addc_co_u32_e32 v47, vcc, 0, v11, vcc
	v_add_co_u32_e32 v10, vcc, s58, v10
	s_nop 0
	s_nop 0
	v_addc_co_u32_e32 v11, vcc, 0, v11, vcc
	global_load_dwordx2 v[46:47], v[46:47], off
	s_nop 0
	global_load_dwordx2 v[10:11], v[10:11], off
	s_waitcnt vmcnt(12)
	v_lshlrev_b32_e32 v49, 16, v19
	v_lshlrev_b32_e32 v48, 16, v18
	v_and_b32_e32 v19, 0xffff0000, v19
	v_and_b32_e32 v18, 0xffff0000, v18
	v_pk_add_f32 v[48:49], v[48:49], 1.0 op_sel_hi:[1,0] neg_lo:[1,0] neg_hi:[1,0]
	v_lshlrev_b32_e32 v51, 16, v21
	v_lshlrev_b32_e32 v50, 16, v20
	v_and_b32_e32 v21, 0xffff0000, v21
	v_and_b32_e32 v20, 0xffff0000, v20
	v_pk_fma_f32 v[6:7], v[6:7], v[48:49], v[18:19]
	v_pk_mul_f32 v[8:9], v[8:9], v[48:49]
	v_pk_add_f32 v[18:19], v[50:51], 1.0 op_sel_hi:[1,0] neg_lo:[1,0] neg_hi:[1,0]
	v_lshlrev_b32_e32 v49, 16, v23
	v_lshlrev_b32_e32 v48, 16, v22
	v_and_b32_e32 v23, 0xffff0000, v23
	v_and_b32_e32 v22, 0xffff0000, v22
	v_pk_fma_f32 v[6:7], v[6:7], v[18:19], v[20:21]
	v_pk_mul_f32 v[8:9], v[8:9], v[18:19]
	v_pk_add_f32 v[18:19], v[48:49], 1.0 op_sel_hi:[1,0] neg_lo:[1,0] neg_hi:[1,0]
	v_lshlrev_b32_e32 v21, 16, v25
	v_lshlrev_b32_e32 v20, 16, v24
	v_and_b32_e32 v25, 0xffff0000, v25
	v_and_b32_e32 v24, 0xffff0000, v24
	v_pk_fma_f32 v[6:7], v[6:7], v[18:19], v[22:23]
	v_pk_mul_f32 v[8:9], v[8:9], v[18:19]
	v_pk_add_f32 v[18:19], v[20:21], 1.0 op_sel_hi:[1,0] neg_lo:[1,0] neg_hi:[1,0]
	s_waitcnt vmcnt(0)
; __device__ __forceinline__ float bf_lo(unsigned w) { return __uint_as_float(w << 16); }
; __device__ __forceinline__ float bf_hi(unsigned w) { return __uint_as_float(w & 0xffff0000u); }
; __device__ __forceinline__ void scan1_own_tiles(const unsigned* AU, float* PA, float* PH) {
;     ...
;             for (int t = 0; t < SCL; ++t) { const u32x2 w = *(const u32x2*)(AU + base + (size_t)t * DM);
;                 const float a0 = 1.0f - bf_lo(w.x), a1 = 1.0f - bf_lo(w.y);
;                 h0 = a0 * h0 + bf_hi(w.x); h1 = a1 * h1 + bf_hi(w.y); p0 *= a0; p1 *= a1; }
;             const size_t o = (size_t)(bb * SCH + cc) * DM + ch;
;             *(f32x2*)(PA + o) = (f32x2){p0, p1}; *(f32x2*)(PH + o) = (f32x2){h0, h1};
	v_lshlrev_b32_e32 v21, 16, v27
	v_lshlrev_b32_e32 v20, 16, v26
	v_and_b32_e32 v23, 0xffff0000, v27
	v_and_b32_e32 v22, 0xffff0000, v26
	v_pk_fma_f32 v[6:7], v[6:7], v[18:19], v[24:25]
	v_pk_mul_f32 v[8:9], v[8:9], v[18:19]
	v_pk_add_f32 v[18:19], v[20:21], 1.0 op_sel_hi:[1,0] neg_lo:[1,0] neg_hi:[1,0]
	v_lshlrev_b32_e32 v21, 16, v29
	v_lshlrev_b32_e32 v20, 16, v28
	v_and_b32_e32 v25, 0xffff0000, v29
	v_and_b32_e32 v24, 0xffff0000, v28
	v_pk_fma_f32 v[6:7], v[6:7], v[18:19], v[22:23]
	v_pk_mul_f32 v[8:9], v[8:9], v[18:19]
	v_pk_add_f32 v[18:19], v[20:21], 1.0 op_sel_hi:[1,0] neg_lo:[1,0] neg_hi:[1,0]
	v_lshlrev_b32_e32 v21, 16, v31
	v_lshlrev_b32_e32 v20, 16, v30
	v_and_b32_e32 v23, 0xffff0000, v31
	v_and_b32_e32 v22, 0xffff0000, v30
	v_pk_fma_f32 v[6:7], v[6:7], v[18:19], v[24:25]
	v_pk_mul_f32 v[8:9], v[8:9], v[18:19]
	v_pk_add_f32 v[18:19], v[20:21], 1.0 op_sel_hi:[1,0] neg_lo:[1,0] neg_hi:[1,0]
	v_lshlrev_b32_e32 v21, 16, v33
	v_lshlrev_b32_e32 v20, 16, v32
	v_and_b32_e32 v25, 0xffff0000, v33
	v_and_b32_e32 v24, 0xffff0000, v32
	v_pk_fma_f32 v[6:7], v[6:7], v[18:19], v[22:23]
	v_pk_mul_f32 v[8:9], v[8:9], v[18:19]
	v_pk_add_f32 v[18:19], v[20:21], 1.0 op_sel_hi:[1,0] neg_lo:[1,0] neg_hi:[1,0]
	v_lshlrev_b32_e32 v21, 16, v35
	v_lshlrev_b32_e32 v20, 16, v34
	v_and_b32_e32 v23, 0xffff0000, v35
	v_and_b32_e32 v22, 0xffff0000, v34
	v_pk_fma_f32 v[6:7], v[6:7], v[18:19], v[24:25]
	v_pk_mul_f32 v[8:9], v[8:9], v[18:19]
	v_pk_add_f32 v[18:19], v[20:21], 1.0 op_sel_hi:[1,0] neg_lo:[1,0] neg_hi:[1,0]
	v_lshlrev_b32_e32 v21, 16, v37
	v_lshlrev_b32_e32 v20, 16, v36
	v_and_b32_e32 v25, 0xffff0000, v37
	v_and_b32_e32 v24, 0xffff0000, v36
	v_pk_fma_f32 v[6:7], v[6:7], v[18:19], v[22:23]
	v_pk_mul_f32 v[8:9], v[8:9], v[18:19]
	v_pk_add_f32 v[18:19], v[20:21], 1.0 op_sel_hi:[1,0] neg_lo:[1,0] neg_hi:[1,0]
	v_lshlrev_b32_e32 v21, 16, v39
	v_lshlrev_b32_e32 v20, 16, v38
	v_and_b32_e32 v23, 0xffff0000, v39
	v_and_b32_e32 v22, 0xffff0000, v38
	v_pk_fma_f32 v[6:7], v[6:7], v[18:19], v[24:25]
	v_pk_mul_f32 v[8:9], v[8:9], v[18:19]
	v_pk_add_f32 v[18:19], v[20:21], 1.0 op_sel_hi:[1,0] neg_lo:[1,0] neg_hi:[1,0]
	v_lshlrev_b32_e32 v21, 16, v41
	v_lshlrev_b32_e32 v20, 16, v40
	v_and_b32_e32 v25, 0xffff0000, v41
	v_and_b32_e32 v24, 0xffff0000, v40
	v_pk_fma_f32 v[6:7], v[6:7], v[18:19], v[22:23]
	v_pk_mul_f32 v[8:9], v[8:9], v[18:19]
	v_pk_add_f32 v[18:19], v[20:21], 1.0 op_sel_hi:[1,0] neg_lo:[1,0] neg_hi:[1,0]
	v_lshlrev_b32_e32 v21, 16, v43
	v_lshlrev_b32_e32 v20, 16, v42
	v_and_b32_e32 v23, 0xffff0000, v43
	v_and_b32_e32 v22, 0xffff0000, v42
	v_pk_fma_f32 v[6:7], v[6:7], v[18:19], v[24:25]
	v_pk_mul_f32 v[8:9], v[8:9], v[18:19]
	v_pk_add_f32 v[18:19], v[20:21], 1.0 op_sel_hi:[1,0] neg_lo:[1,0] neg_hi:[1,0]
	v_lshlrev_b32_e32 v21, 16, v45
	v_lshlrev_b32_e32 v20, 16, v44
	v_and_b32_e32 v25, 0xffff0000, v45
	v_and_b32_e32 v24, 0xffff0000, v44
	v_pk_fma_f32 v[6:7], v[6:7], v[18:19], v[22:23]
	v_pk_mul_f32 v[8:9], v[8:9], v[18:19]
	v_pk_add_f32 v[18:19], v[20:21], 1.0 op_sel_hi:[1,0] neg_lo:[1,0] neg_hi:[1,0]
	v_lshlrev_b32_e32 v21, 16, v47
	v_lshlrev_b32_e32 v20, 16, v46
	v_and_b32_e32 v23, 0xffff0000, v47
	v_and_b32_e32 v22, 0xffff0000, v46
	v_pk_fma_f32 v[6:7], v[6:7], v[18:19], v[24:25]
	v_pk_mul_f32 v[8:9], v[8:9], v[18:19]
	v_pk_add_f32 v[18:19], v[20:21], 1.0 op_sel_hi:[1,0] neg_lo:[1,0] neg_hi:[1,0]
	v_lshlrev_b32_e32 v21, 16, v11
	v_lshlrev_b32_e32 v20, 16, v10
	v_and_b32_e32 v11, 0xffff0000, v11
	v_and_b32_e32 v10, 0xffff0000, v10
	v_pk_fma_f32 v[6:7], v[6:7], v[18:19], v[22:23]
	v_pk_mul_f32 v[8:9], v[8:9], v[18:19]
	v_pk_add_f32 v[18:19], v[20:21], 1.0 op_sel_hi:[1,0] neg_lo:[1,0] neg_hi:[1,0]
	s_nop 0
	v_pk_fma_f32 v[6:7], v[6:7], v[18:19], v[10:11]
	v_pk_mul_f32 v[8:9], v[8:9], v[18:19]
	s_cbranch_scc0 .LBB0_959
	v_lshl_or_b32 v4, v16, 1, v13
	v_ashrrev_i32_e32 v5, 31, v4
	v_lshlrev_b64 v[4:5], 11, v[4:5]
	v_lshl_add_u64 v[2:3], v[4:5], 0, v[2:3]
	v_lshlrev_b64 v[2:3], 2, v[2:3]
	v_lshl_add_u64 v[4:5], s[0:1], 0, v[2:3]
	v_lshl_add_u64 v[2:3], s[2:3], 0, v[2:3]
	global_store_dwordx2 v[4:5], v[8:9], off
	global_store_dwordx2 v[2:3], v[6:7], off
	s_branch .LBB0_950
